# mLSTM chain: prefetch issued at chunk top; wave-0 gate prefix sum/max scans via DPP row_shr/row_bcast instead of 12 ds_bpermute round trips (f32, summation order differs)
# speedup vs baseline: 1.0764x; 1.0198x over previous
; #define LAS __attribute__((address_space(3)))
; __device__ __forceinline__ void mlstm_task(const Ctx& c, int p, int l, int q, int h, int slab) {
;     ...
; #pragma unroll
;         for (int i = 0; i < 4; ++i) {
;             const int piece = tid + 512 * i, t = piece >> 5, pc = piece & 31;
;             *(LAS u32x4*)(Qs + t * 264 + 8 * pc) = pq[i]; *(LAS u32x4*)(Ks + t * 264 + 8 * pc) = pk[i];
;         }
;         *(LAS u32x4*)(St + (tid >> 3) * 72 + 8 * (tid & 7)) = psl;
;         if (tid < 256) {
;             const int t = tid >> 2, pc = tid & 3; const u32x4 vv = pvv;
;             const unsigned vw[4] = {vv.x, vv.y, vv.z, vv.w};
; #pragma unroll
;             for (int e = 0; e < 4; ++e) { VT[(8 * pc + 2 * e) * 72 + t] = (bf16_t)(vw[e] & 0xffffu); VT[(8 * pc + 2 * e + 1) * 72 + t] = (bf16_t)(vw[e] >> 16); }
;         }
.LBB0_1584:
	s_waitcnt vmcnt(0)
	s_and_saveexec_b64 s[68:69], s[14:15]
	s_cbranch_execz .Lml_top_a
	ds_write_b16 v97, v56
	ds_write_b16_d16_hi v97, v56 offset:144
	ds_write_b16 v97, v57 offset:288
	ds_write_b16_d16_hi v97, v57 offset:432
	ds_write_b16 v97, v58 offset:576
	ds_write_b16_d16_hi v97, v58 offset:720
	ds_write_b16 v97, v59 offset:864
	ds_write_b16_d16_hi v97, v59 offset:1008
.Lml_top_a:
	s_or_b64 exec, exec, s[68:69]
	ds_write_b128 v96, v[14:17]
	ds_write_b128 v96, v[40:43] offset:33792
	ds_write_b128 v98, v[18:21]
	ds_write_b128 v98, v[44:47] offset:33792
	ds_write_b128 v100, v[22:25]
	ds_write_b128 v100, v[52:55] offset:33792
	ds_write_b128 v102, v[26:29]
	ds_write_b128 v102, v[64:67] offset:33792
	ds_write_b128 v118, v[36:39]
	s_cmpk_gt_u32 s75, 0x7e
	s_cbranch_scc1 .Lml_top_b
	s_ashr_i32 s81, s80, 31
	s_lshl_b64 s[68:69], s[80:81], 13
	v_lshl_add_u64 v[0:1], v[92:93], 0, s[68:69]
	global_load_dwordx4 v[36:39], v[0:1], off
	v_mov_b64_e32 v[40:41], v[32:33]
	v_mov_b64_e32 v[42:43], v[34:35]
	v_mov_b64_e32 v[44:45], v[32:33]
	v_mov_b64_e32 v[46:47], v[34:35]
	v_mov_b64_e32 v[52:53], v[32:33]
	v_mov_b64_e32 v[54:55], v[34:35]
	v_mov_b64_e32 v[64:65], v[32:33]
	v_mov_b64_e32 v[66:67], v[34:35]
	v_mov_b64_e32 v[14:15], v[32:33]
	v_mov_b64_e32 v[16:17], v[34:35]
	v_mov_b64_e32 v[18:19], v[32:33]
	v_mov_b64_e32 v[20:21], v[34:35]
	v_mov_b64_e32 v[22:23], v[32:33]
	v_mov_b64_e32 v[24:25], v[34:35]
	v_mov_b64_e32 v[26:27], v[32:33]
	v_mov_b64_e32 v[28:29], v[34:35]
	s_and_saveexec_b64 s[68:69], s[4:5]
	s_cbranch_execz .Lml_pf1
	v_add_u32_e32 v1, s96, v187
	v_mov_b64_e32 v[2:3], s[72:73]
	v_mad_i64_i32 v[2:3], s[86:87], v1, s33, v[2:3]
	s_lshl_b32 s90, s88, 1
	v_lshl_add_u64 v[2:3], v[2:3], 0, s[90:91]
	v_lshl_add_u64 v[0:1], v[2:3], 0, v[30:31]
	v_add_co_u32_e32 v2, vcc, 0x1000, v0
	s_nop 1
	v_addc_co_u32_e32 v3, vcc, 0, v1, vcc
	global_load_dwordx4 v[14:17], v[0:1], off offset:2048
	global_load_dwordx4 v[40:43], v[2:3], off

; __device__ __forceinline__ void mlstm_task(const Ctx& c, int p, int l, int q, int h, int slab) {
;     ...
;         if (w == 0) {
;             const int t = lane; float ig = -1e30f, lf = 0.f;
;             if (t < nvalid) { ig = pgi + bi; const float gf = pgf + bf; lf = fminf(gf, 0.f) - __logf(1.0f + __expf(-fabsf(gf))); }
.Lml_top_b:
	s_andn2_b64 vcc, exec, s[76:77]
	s_cbranch_vccnz .LBB0_1640

; __device__ __forceinline__ bf16_t f2bf(float f) { unsigned u = __float_as_uint(f); u += 0x7FFFu + ((u >> 16) & 1u); return (bf16_t)(u >> 16); }
; __device__ __forceinline__ void mlstm_task(const Ctx& c, int p, int l, int q, int h, int slab) {
;     ...
;         if (w == 0) {
;             const int t = lane; float ig = -1e30f, lf = 0.f;
;             if (t < nvalid) { ig = pgi + bi; const float gf = pgf + bf; lf = fminf(gf, 0.f) - __logf(1.0f + __expf(-fabsf(gf))); }
;             float bc = lf;
; #pragma unroll
;             for (int o = 1; o < 64; o <<= 1) { const float u = __shfl_up(bc, o); if (lane >= o) bc += u; }
;             float cm = ig - bc;
; #pragma unroll
;             for (int o = 1; o < 64; o <<= 1) { const float u = __shfl_up(cm, o); if (lane >= o) cm = fmaxf(cm, u); }
;             const float mprev = misc[0];
;             const float mt = bc + fmaxf(mprev, cm);
;             const float wi = __expf(bc + mprev - mt);
;             const float bL = __shfl(bc, 63), mnew = __shfl(mt, 63);
;             const float gs_ = __expf(bL - bc + ig - mnew);
;             mts[t] = mt; wint[t] = wi; gsrc[t] = gs_; VgT[32 * 72 + t] = f2bf(gs_); esc[t] = __expf(cm - fmaxf(mprev, cm));
;             if (lane == 0) { misc[1] = __expf(bL + mprev - mnew); misc[2] = mnew; }
;         }
.LBB0_1588:
	s_or_b64 exec, exec, s[86:87]
	v_mov_b32_e32 v8, v1
	s_nop 1
	v_add_f32_dpp v8, v8, v8 row_shr:1 row_mask:0xf bank_mask:0xf
	s_nop 1
	v_add_f32_dpp v8, v8, v8 row_shr:2 row_mask:0xf bank_mask:0xf
	s_nop 1
	v_add_f32_dpp v8, v8, v8 row_shr:4 row_mask:0xf bank_mask:0xf
	s_nop 1
	v_add_f32_dpp v8, v8, v8 row_shr:8 row_mask:0xf bank_mask:0xf
	s_nop 1
	v_add_f32_dpp v8, v8, v8 row_bcast:15 row_mask:0xa bank_mask:0xf
	s_nop 1
	v_add_f32_dpp v8, v8, v8 row_bcast:31 row_mask:0xc bank_mask:0xf
	v_mov_b32_e32 v1, s0
	ds_read_b32 v1, v1
	v_sub_f32_e32 v4, v0, v8
	s_nop 1
	v_max_f32_dpp v4, v4, v4 row_shr:1 row_mask:0xf bank_mask:0xf
	s_nop 1
	v_max_f32_dpp v4, v4, v4 row_shr:2 row_mask:0xf bank_mask:0xf
	s_nop 1
	v_max_f32_dpp v4, v4, v4 row_shr:4 row_mask:0xf bank_mask:0xf
	s_nop 1
	v_max_f32_dpp v4, v4, v4 row_shr:8 row_mask:0xf bank_mask:0xf
	s_nop 1
	v_max_f32_dpp v4, v4, v4 row_bcast:15 row_mask:0xa bank_mask:0xf
	s_nop 1
	v_max_f32_dpp v4, v4, v4 row_bcast:31 row_mask:0xc bank_mask:0xf
	v_readlane_b32 s68, v8, 63
	s_waitcnt lgkmcnt(0)
	v_max_f32_e32 v2, v4, v4
	v_max_f32_e32 v3, v1, v1
	v_max_f32_e32 v5, v3, v2
	v_add_f32_e32 v6, v8, v5
	v_add_f32_e32 v2, v1, v8
	v_sub_f32_e32 v2, v2, v6
	v_mul_f32_e32 v2, 0x3fb8aa3b, v2
	v_exp_f32_e32 v7, v2
	v_readlane_b32 s69, v6, 63
	v_mov_b32_e32 v3, s68
	v_sub_f32_e32 v8, v3, v8
	v_add_f32_e32 v0, v0, v8
	v_mov_b32_e32 v2, s69
	v_sub_f32_e32 v0, v0, v2
	v_mul_f32_e32 v0, 0x3fb8aa3b, v0
	v_exp_f32_e32 v0, v0
	ds_write_b32 v126, v6
	ds_write_b32 v127, v7
	ds_write_b32 v128, v0
	v_bfe_u32 v6, v0, 16, 1
	v_add3_u32 v0, v0, v6, s1
	ds_write_b16_d16_hi v129, v0 offset:4608
	v_sub_f32_e32 v0, v4, v5
	v_mul_f32_e32 v0, 0x3fb8aa3b, v0
	v_exp_f32_e32 v0, v0
	ds_write_b32 v130, v0
	s_and_saveexec_b64 s[68:69], s[28:29]
	s_cbranch_execz .LBB0_1590
	v_add_f32_e32 v0, v1, v3
	v_sub_f32_e32 v0, v0, v2
	v_mul_f32_e32 v0, 0x3fb8aa3b, v0
	v_exp_f32_e32 v0, v0
	v_mov_b32_e32 v1, s93
	ds_write2_b32 v1, v0, v2 offset1:1

; __device__ __forceinline__ void mlstm_task(const Ctx& c, int p, int l, int q, int h, int slab) {
;     ...
;         __syncthreads();
;         if (ck + 1 < nch) ML_PREFETCH(rbase + 64);
.LBB0_1615:
	s_or_b64 exec, exec, s[68:69]
	s_cmpk_gt_u32 s75, 0x7e
	s_waitcnt lgkmcnt(0)
	s_barrier
	s_cbranch_scc1 .LBB0_1629
	s_and_saveexec_b64 s[68:69], s[78:79]
	s_cbranch_execz .LBB0_1628
	v_add_u32_e32 v0, s96, v186
	v_ashrrev_i32_e32 v1, 31, v0
	v_lshlrev_b64 v[0:1], 5, v[0:1]
	v_lshl_add_u64 v[0:1], v[94:95], 0, v[0:1]
	global_load_dword v116, v[0:1], off
	global_load_dword v117, v[0:1], off offset:16

; __device__ __forceinline__ bf16_t f2bf(float f) { unsigned u = __float_as_uint(f); u += 0x7FFFu + ((u >> 16) & 1u); return (bf16_t)(u >> 16); }
; __device__ __forceinline__ void mlstm_task(const Ctx& c, int p, int l, int q, int h, int slab) {
;     ...
;         for (int r = 0; r < 4; ++r) {
;             const int t = 16 * ti + (lane >> 4) * 4 + r;
;             if (t < nvalid) Z[(size_t)(rbase + t) * ZW + C_V + 256 * h + slab * 32 + 16 * vj + (lane & 15)] = f2bf(num[r] * __builtin_amdgcn_rcpf(dd[t]));
;         }
.LBB0_1638:
	ds_read_b32 v1, v161
	v_mul_f32_e32 v0, v6, v108
	v_fmac_f32_e32 v0, v2, v106
	v_add3_u32 v4, v191, s96, 2
	s_lshl_b32 s90, s88, 1
	s_waitcnt lgkmcnt(0)
	v_rcp_f32_e32 v1, v1
	v_mov_b32_e32 v9, v31
	v_mul_f32_e32 v0, v0, v1
	v_bfe_u32 v1, v0, 16, 1
	v_add3_u32 v2, v0, v1, s1
	v_mov_b64_e32 v[0:1], s[72:73]
	v_mad_i64_i32 v[0:1], s[86:87], v4, s33, v[0:1]
	v_lshl_add_u64 v[0:1], v[0:1], 0, s[90:91]
	s_lshl_b32 s90, s92, 1
	v_lshl_add_u64 v[0:1], v[0:1], 0, s[90:91]
	s_lshl_b32 s90, s71, 1
	v_lshl_add_u64 v[0:1], v[0:1], 0, s[90:91]
	v_lshl_add_u64 v[0:1], v[0:1], 0, v[8:9]
	v_add_co_u32_e32 v0, vcc, 0x1000, v0
	s_nop 1
	v_addc_co_u32_e32 v1, vcc, 0, v1, vcc
	global_store_short_d16_hi v[0:1], v2, off offset:2048
	s_or_b64 exec, exec, s[68:69]
	s_and_saveexec_b64 s[68:69], s[66:67]
	s_cbranch_execnz .LBB0_1667
	s_branch .LBB0_1668
.LBB0_1640:
	s_and_saveexec_b64 s[68:69], s[44:45]
	s_cbranch_execz .LBB0_1591
